# nt policy extended: read-once projection scratch loads in the gate epilogue and the final output stores
# baseline (speedup 1.0000x reference)
;     template <int NM> __device__ __forceinline__ void round(const AccT& acc, const Unit& u, int ai, int m0, int wr, int wc, int fr, int fq) const {
;         u32x4 hv[NM][2], pv[NM][2]; u32x2 lv[NM][2];
; #pragma unroll
;         for (int mm = 0; mm < NM; ++mm) {
;             const int rl = ai * 128 + wr * 64 + (m0 + mm) * 16 + fr;
;             const size_t off = (size_t)(u.pm * 256 + rl) * DM + u.pn * 256 + wc * 32 + 8 * fq;
; #pragma unroll
;             for (int bj = 0; bj < 2; ++bj) {
;                 hv[mm][bj] = *GP(const u32x4, hin + off + bj * 128); lv[mm][bj] = (u32x2){0u, 0u};
;                 if (MODE == 1) pv[mm][bj] = *GP(const u32x4, proj + off + bj * 128);
;             }
;         }
; #pragma unroll
;         for (int mm = 0; mm < NM; ++mm) {
;             const int m = m0 + mm;
;             const int rl = ai * 128 + wr * 64 + m * 16 + fr; const int row = u.pm * 256 + rl;
;             const size_t off = (size_t)row * DM + u.pn * 256 + wc * 32 + 8 * fq;
;             float r = 1.f; if (MODE == 1) r = rs[((u.pm >> 3) & 3) * 256 + rl];
.LBB0_577:
	s_lshl_b32 s26, s81, 2
	s_add_i32 s26, s26, s25
	s_lshl_b32 s26, s26, 17
	s_mov_b32 s27, 0
	v_and_b32_e32 v176, 0xffffffc0, v162
	v_lshlrev_b32_e32 v176, 8, v176
	v_lshl_add_u32 v176, v208, 4, v176
	v_mov_b32_e32 v177, 0
	v_lshl_add_u64 v[176:177], s[26:27], 0, v[176:177]
	v_lshl_add_u64 v[176:177], s[18:19], 0, v[176:177]
	s_lshl_b32 s46, s81, 8
	v_add_u32_e32 v192, s46, v148
	s_lshl_b32 s16, s25, 8
	s_ashr_i32 s17, s16, 31
	v_ashrrev_i32_e32 v193, 31, v192
	v_mov_b32_e32 v159, s17
	v_or_b32_e32 v158, s16, v150
	v_lshlrev_b64 v[128:129], 10, v[192:193]
	v_lshl_add_u64 v[128:129], v[128:129], 0, v[158:159]
	v_lshlrev_b64 v[128:129], 1, v[128:129]
	v_mov_b64_e32 v[130:131], v[176:177]
	v_lshl_add_u64 v[128:129], s[66:67], 0, v[128:129]
	global_load_dwordx4 v[212:215], v[130:131], off nt
	global_load_dwordx4 v[216:219], v[128:129], off
	s_lshl_b32 s12, s81, 7
	s_and_b32 s12, s12, 0xc00
	s_add_i32 s12, s12, 0
	s_add_i32 s12, s12, 0x20000
	v_lshl_add_u32 v205, v148, 2, s12
	ds_read_b32 v224, v205
	global_load_dwordx4 v[144:147], v[128:129], off offset:256
	global_load_dwordx4 v[220:223], v[130:131], off offset:1024 nt
	v_and_b32_e32 v132, 64, v163
	v_xor_b32_e32 v133, 16, v163
	v_add_u32_e32 v135, 64, v132
	v_or_b32_e32 v132, 16, v192
	v_cmp_lt_i32_e32 vcc, v133, v135
	v_xor_b32_e32 v134, 32, v163
	s_waitcnt lgkmcnt(0)
	v_pk_mul_f32 v[122:123], v[122:123], v[224:225] op_sel_hi:[1,0]
	v_cndmask_b32_e32 v136, v163, v133, vcc
	v_ashrrev_i32_e32 v133, 31, v132
	v_lshlrev_b64 v[132:133], 10, v[132:133]
	v_lshl_add_u64 v[132:133], v[132:133], 0, v[158:159]
	v_cmp_lt_i32_e32 vcc, v134, v135
	v_lshlrev_b64 v[132:133], 1, v[132:133]
	v_lshl_add_u64 v[128:129], s[66:67], 0, v[132:133]
	v_cndmask_b32_e32 v134, v163, v134, vcc
	s_mov_b64 s[26:27], 0x800
	v_lshl_add_u64 v[132:133], v[176:177], 0, s[26:27]
	v_lshlrev_b32_e32 v204, 2, v136
	v_lshlrev_b32_e32 v203, 2, v134
	global_load_dwordx4 v[136:139], v[128:129], off
	s_nop 0
	global_load_dwordx4 v[128:131], v[128:129], off offset:256
	s_nop 0
	global_load_dwordx4 v[140:143], v[132:133], off nt
	s_nop 0
	global_load_dwordx4 v[132:135], v[132:133], off offset:1024 nt
	v_pk_mul_f32 v[120:121], v[120:121], v[224:225] op_sel_hi:[1,0]
	v_pk_mul_f32 v[126:127], v[126:127], v[224:225] op_sel_hi:[1,0]
	v_pk_mul_f32 v[124:125], v[124:125], v[224:225] op_sel_hi:[1,0]
	v_mul_f32_e32 v120, 0xbfb8aa3b, v120
	v_mul_f32_e32 v121, 0xbfb8aa3b, v121
	v_mul_f32_e32 v122, 0xbfb8aa3b, v122
	v_mul_f32_e32 v123, 0xbfb8aa3b, v123
	v_mul_f32_e32 v124, 0xbfb8aa3b, v124
	v_mul_f32_e32 v125, 0xbfb8aa3b, v125
	v_mul_f32_e32 v126, 0xbfb8aa3b, v126
	v_mul_f32_e32 v127, 0xbfb8aa3b, v127
	v_exp_f32_e32 v120, v120
	v_exp_f32_e32 v121, v121
	v_exp_f32_e32 v122, v122
	v_exp_f32_e32 v123, v123
	v_exp_f32_e32 v124, v124
	v_exp_f32_e32 v125, v125
	v_exp_f32_e32 v126, v126
	v_exp_f32_e32 v127, v127
	v_add_f32_e32 v120, 1.0, v120
	v_add_f32_e32 v121, 1.0, v121
	v_add_f32_e32 v122, 1.0, v122
	v_add_f32_e32 v123, 1.0, v123
	v_add_f32_e32 v124, 1.0, v124
	v_add_f32_e32 v125, 1.0, v125
	v_add_f32_e32 v126, 1.0, v126
	v_add_f32_e32 v127, 1.0, v127
	v_rcp_f32_e32 v226, v120
	v_rcp_f32_e32 v227, v121
	v_rcp_f32_e32 v228, v122
	v_rcp_f32_e32 v229, v123
	v_cvt_pk_f32_fp8_e32 v[120:121], 0
	v_cvt_pk_f32_fp8_sdwa v[122:123], s63 src0_sel:WORD_1
	v_rcp_f32_e32 v124, v124
	v_rcp_f32_e32 v125, v125
	v_rcp_f32_e32 v126, v126
	v_rcp_f32_e32 v127, v127
	v_pk_mul_f32 v[118:119], v[118:119], v[224:225] op_sel_hi:[1,0]
	v_pk_mul_f32 v[116:117], v[116:117], v[224:225] op_sel_hi:[1,0]
	v_mul_f32_e32 v118, 0xbfb8aa3b, v118
	v_mul_f32_e32 v119, 0xbfb8aa3b, v119
	v_mul_f32_e32 v116, 0xbfb8aa3b, v116
	v_mul_f32_e32 v117, 0xbfb8aa3b, v117
	v_pk_mul_f32 v[112:113], v[112:113], v[224:225] op_sel_hi:[1,0]
	v_exp_f32_e32 v118, v118
	v_exp_f32_e32 v119, v119
	v_exp_f32_e32 v116, v116
	v_exp_f32_e32 v117, v117
	v_mul_f32_e32 v112, 0xbfb8aa3b, v112
	v_mul_f32_e32 v113, 0xbfb8aa3b, v113
	v_exp_f32_e32 v112, v112
	v_exp_f32_e32 v113, v113
	s_waitcnt vmcnt(0)
; __device__ __forceinline__ unsigned cvt_pk_bf16(float lo, float hi) { const f32x2 v = {lo, hi}; return __builtin_bit_cast(unsigned, __builtin_convertvector(v, bfx2_t)); }
; __device__ __forceinline__ float bflo(unsigned w) { return __uint_as_float(w << 16); }
; __device__ __forceinline__ float bfhi(unsigned w) { return __uint_as_float(w & 0xffff0000u); }
; __device__ __forceinline__ unsigned lo_pack4(float a, float b, float c, float d) { int p = __builtin_amdgcn_cvt_pk_fp8_f32(a * 512.0f, b * 512.0f, 0, false); return (unsigned)__builtin_amdgcn_cvt_pk_fp8_f32(c * 512.0f, d * 512.0f, p, true); }
;     template <int NM> __device__ __forceinline__ void round(const AccT& acc, const Unit& u, int ai, int m0, int wr, int wc, int fr, int fq) const {
;     ...
;                     const u32x4 p = pv[mm][bj];
;                     const f32x4 a0 = acc[ai][bj][m][0] * r, a1 = acc[ai][bj][m][1] * r;
;                     d0 = (f32x4){fsigmoid(a0[0]) * bflo(p.x), fsigmoid(a0[1]) * bfhi(p.x), fsigmoid(a0[2]) * bflo(p.y), fsigmoid(a0[3]) * bfhi(p.y)};
;                     d1 = (f32x4){fsigmoid(a1[0]) * bflo(p.z), fsigmoid(a1[1]) * bfhi(p.z), fsigmoid(a1[2]) * bflo(p.w), fsigmoid(a1[3]) * bfhi(p.w)};
;                 }
;                 const u32x4 H = hv[mm][bj]; const u32x2 L = lv[mm][bj];
;                 const f32x4 o0 = ((f32x4){bflo(H.x), bfhi(H.x), bflo(H.y), bfhi(H.y)} + lo_unpack4(L.x)) + d0;
;                 const f32x4 o1 = ((f32x4){bflo(H.z), bfhi(H.z), bflo(H.w), bfhi(H.w)} + lo_unpack4(L.y)) + d1;
;                 u32x4 w; w.x = cvt_pk_bf16(o0[0], o0[1]); w.y = cvt_pk_bf16(o0[2], o0[3]); w.z = cvt_pk_bf16(o1[0], o1[1]); w.w = cvt_pk_bf16(o1[2], o1[3]);
;                 u32x2 wl; wl.x = lo_pack4(o0[0] - bflo(w.x), o0[1] - bfhi(w.x), o0[2] - bflo(w.y), o0[3] - bfhi(w.y));
;                 wl.y = lo_pack4(o1[0] - bflo(w.z), o1[1] - bfhi(w.z), o1[2] - bflo(w.w), o1[3] - bfhi(w.w));
;                 *GP(u32x4, hout + off + bj * 128) = w; (void)wl;
;                 ss += (o0[0] * o0[0] + o0[1] * o0[1]) + (o0[2] * o0[2] + o0[3] * o0[3]) + (o1[0] * o1[0] + o1[1] * o1[1]) + (o1[2] * o1[2] + o1[3] * o1[3]);
;             }
;             ss += __shfl_xor(ss, 16); ss += __shfl_xor(ss, 32);
;             if (fq == 0) *GP(float, ssp + (size_t)(u.pn * 4 + wc) * TT + row) = ss;
	v_lshlrev_b32_e32 v230, 16, v212
	v_lshlrev_b32_e32 v234, 16, v216
	v_and_b32_e32 v235, 0xffff0000, v216
	v_lshlrev_b32_e32 v216, 16, v217
	v_and_b32_e32 v217, 0xffff0000, v217
	v_and_b32_e32 v231, 0xffff0000, v212
	v_lshlrev_b32_e32 v212, 16, v213
	v_and_b32_e32 v213, 0xffff0000, v213
	v_pk_fma_f32 v[234:235], v[120:121], s[34:35], v[234:235] op_sel_hi:[1,0,1]
	v_pk_fma_f32 v[216:217], v[122:123], s[34:35], v[216:217] op_sel_hi:[1,0,1]
	v_lshlrev_b32_e32 v232, 16, v214
	v_pk_fma_f32 v[212:213], v[126:127], v[212:213], v[216:217]
	v_pk_fma_f32 v[216:217], v[124:125], v[230:231], v[234:235]
	v_lshlrev_b32_e32 v124, 16, v218
	v_and_b32_e32 v125, 0xffff0000, v218
	v_and_b32_e32 v233, 0xffff0000, v214
	v_pk_fma_f32 v[124:125], v[120:121], s[34:35], v[124:125] op_sel_hi:[1,0,1]
	v_lshlrev_b32_e32 v126, 16, v219
	v_and_b32_e32 v127, 0xffff0000, v219
	v_pk_fma_f32 v[218:219], v[226:227], v[232:233], v[124:125]
	v_cvt_pk_bf16_f32 v125, v212, v213
	v_mul_f32_e32 v211, v217, v217
	v_mul_f32_e32 v213, v213, v213
	v_lshlrev_b32_e32 v214, 16, v215
	v_and_b32_e32 v215, 0xffff0000, v215
	v_pk_fma_f32 v[126:127], v[122:123], s[34:35], v[126:127] op_sel_hi:[1,0,1]
	v_fmac_f32_e32 v211, v216, v216
	v_fmac_f32_e32 v213, v212, v212
	v_mul_f32_e32 v212, v219, v219
	v_pk_mul_f32 v[114:115], v[114:115], v[224:225] op_sel_hi:[1,0]
	v_pk_fma_f32 v[214:215], v[228:229], v[214:215], v[126:127]
	v_add_f32_e32 v211, v211, v213
	v_fmac_f32_e32 v212, v218, v218
	v_add_f32_e32 v118, 1.0, v118
	v_add_f32_e32 v119, 1.0, v119
	v_mul_f32_e32 v114, 0xbfb8aa3b, v114
	v_mul_f32_e32 v115, 0xbfb8aa3b, v115
	v_add_f32_e32 v211, v212, v211
	v_mul_f32_e32 v212, v215, v215
	v_add_f32_e32 v116, 1.0, v116
	v_add_f32_e32 v117, 1.0, v117
	v_rcp_f32_e32 v118, v118
	v_rcp_f32_e32 v119, v119
	v_exp_f32_e32 v114, v114
	v_exp_f32_e32 v115, v115
	v_fmac_f32_e32 v212, v214, v214
	v_rcp_f32_e32 v116, v116
	v_rcp_f32_e32 v117, v117
	v_add_f32_e32 v112, 1.0, v112
	v_add_f32_e32 v113, 1.0, v113
	v_cvt_pk_bf16_f32 v127, v214, v215
	v_add_f32_e32 v211, v212, v211
	v_lshlrev_b32_e32 v212, 16, v220
	v_and_b32_e32 v213, 0xffff0000, v220
	v_lshlrev_b32_e32 v214, 16, v221
	v_and_b32_e32 v215, 0xffff0000, v221
	v_rcp_f32_e32 v112, v112
	v_rcp_f32_e32 v113, v113
	v_lshlrev_b32_e32 v220, 16, v144
	v_and_b32_e32 v221, 0xffff0000, v144
	v_lshlrev_b32_e32 v144, 16, v145
	v_and_b32_e32 v145, 0xffff0000, v145
	v_pk_fma_f32 v[144:145], v[122:123], s[34:35], v[144:145] op_sel_hi:[1,0,1]
	v_add_f32_e32 v114, 1.0, v114
	v_add_f32_e32 v115, 1.0, v115
	v_pk_fma_f32 v[220:221], v[120:121], s[34:35], v[220:221] op_sel_hi:[1,0,1]
	v_pk_fma_f32 v[118:119], v[118:119], v[214:215], v[144:145]
	v_lshlrev_b32_e32 v144, 16, v146
	v_and_b32_e32 v145, 0xffff0000, v146
	v_cvt_pk_bf16_f32 v124, v216, v217
	v_lshlrev_b32_e32 v216, 16, v222
	v_and_b32_e32 v217, 0xffff0000, v222
	v_rcp_f32_e32 v114, v114
	v_rcp_f32_e32 v115, v115
	v_pk_fma_f32 v[116:117], v[116:117], v[212:213], v[220:221]
	v_pk_fma_f32 v[144:145], v[120:121], s[34:35], v[144:145] op_sel_hi:[1,0,1]
	v_lshlrev_b32_e32 v146, 16, v147
	v_pk_fma_f32 v[144:145], v[112:113], v[216:217], v[144:145]
	v_mul_f32_e32 v112, v117, v117
	v_mul_f32_e32 v113, v119, v119
	v_and_b32_e32 v147, 0xffff0000, v147
	v_fmac_f32_e32 v112, v116, v116
	v_fmac_f32_e32 v113, v118, v118
	v_cvt_pk_bf16_f32 v126, v218, v219
	v_lshlrev_b32_e32 v218, 16, v223
	v_and_b32_e32 v219, 0xffff0000, v223
	v_pk_fma_f32 v[146:147], v[122:123], s[34:35], v[146:147] op_sel_hi:[1,0,1]
	v_add_f32_e32 v112, v112, v113
	v_mul_f32_e32 v113, v145, v145
	v_pk_fma_f32 v[146:147], v[114:115], v[218:219], v[146:147]
	v_fmac_f32_e32 v113, v144, v144
	v_add_f32_e32 v112, v113, v112
	v_mul_f32_e32 v113, v147, v147
	v_fmac_f32_e32 v113, v146, v146
	v_add_f32_e32 v112, v113, v112
	v_add_f32_e32 v115, v211, v112
	v_mov_b32_e32 v211, v115
	s_nop 1
	v_permlane16_swap_b32_e32 v115, v211
	v_lshlrev_b64 v[206:207], 11, v[192:193]
	v_lshl_add_u64 v[206:207], s[14:15], 0, v[206:207]
	v_lshl_add_u64 v[206:207], s[16:17], 1, v[206:207]
	v_lshl_add_u64 v[112:113], v[206:207], 0, s[62:63]
	v_lshl_add_u64 v[206:207], v[112:113], 0, v[168:169]
	s_waitcnt lgkmcnt(0)
	v_add_f32_e32 v112, v115, v211
	v_mov_b32_e32 v113, v112
	s_nop 1
	v_permlane32_swap_b32_e32 v112, v113
	v_cvt_pk_bf16_f32 v114, v116, v117
	v_cvt_pk_bf16_f32 v115, v118, v119
	v_cvt_pk_bf16_f32 v116, v144, v145
	v_cvt_pk_bf16_f32 v117, v146, v147
	global_store_dwordx4 v[206:207], v[124:127], off
	global_store_dwordx4 v[206:207], v[114:117], off offset:256
	s_and_saveexec_b64 s[12:13], s[42:43]
	s_cbranch_execz .LBB0_579
	s_lshl_b32 s20, s25, 2
	s_or_b32 s20, s20, s71
	s_ashr_i32 s21, s20, 31
	s_lshl_b64 s[20:21], s[20:21], 18
	s_add_u32 s20, s65, s20
	s_addc_u32 s21, s70, s21
	s_waitcnt lgkmcnt(0)
	v_add_f32_e32 v114, v112, v113
	v_lshl_add_u64 v[112:113], v[192:193], 2, s[20:21]
	global_store_dword v[112:113], v114, off

;     template <int NM> __device__ __forceinline__ void round(const AccT& acc, const Unit& u, int ai, int m0, int wr, int wc, int fr, int fq) const {
;         u32x4 hv[NM][2], pv[NM][2]; u32x2 lv[NM][2];
; #pragma unroll
;         for (int mm = 0; mm < NM; ++mm) {
;             const int rl = ai * 128 + wr * 64 + (m0 + mm) * 16 + fr;
;             const size_t off = (size_t)(u.pm * 256 + rl) * DM + u.pn * 256 + wc * 32 + 8 * fq;
; #pragma unroll
;             for (int bj = 0; bj < 2; ++bj) {
;                 hv[mm][bj] = *GP(const u32x4, hin + off + bj * 128); lv[mm][bj] = (u32x2){0u, 0u};
;                 if (MODE == 1) pv[mm][bj] = *GP(const u32x4, proj + off + bj * 128);
;             }
;         }
; #pragma unroll
;         for (int mm = 0; mm < NM; ++mm) {
;             const int m = m0 + mm;
;             const int rl = ai * 128 + wr * 64 + m * 16 + fr; const int row = u.pm * 256 + rl;
;             const size_t off = (size_t)row * DM + u.pn * 256 + wc * 32 + 8 * fq;
;             float r = 1.f; if (MODE == 1) r = rs[((u.pm >> 3) & 3) * 256 + rl];
.LBB0_581:
	s_or_b64 exec, exec, s[12:13]
	v_or_b32_e32 v96, 32, v192
	s_waitcnt lgkmcnt(0)
	v_ashrrev_i32_e32 v97, 31, v96
	v_lshlrev_b64 v[96:97], 10, v[96:97]
	v_lshl_add_u64 v[96:97], v[96:97], 0, v[158:159]
	v_lshlrev_b64 v[96:97], 1, v[96:97]
	v_lshl_add_u64 v[98:99], s[66:67], 0, v[96:97]
	s_mov_b64 s[26:27], 0x1000
	v_lshl_add_u64 v[96:97], v[176:177], 0, s[26:27]
	global_load_dwordx4 v[120:123], v[98:99], off
	global_load_dwordx4 v[124:127], v[96:97], off nt
	global_load_dwordx4 v[112:115], v[98:99], off offset:256
	global_load_dwordx4 v[116:119], v[96:97], off offset:1024 nt
	v_or_b32_e32 v96, 48, v192
	v_ashrrev_i32_e32 v97, 31, v96
	v_lshlrev_b64 v[96:97], 10, v[96:97]
	v_lshl_add_u64 v[96:97], v[96:97], 0, v[158:159]
	v_lshlrev_b64 v[96:97], 1, v[96:97]
	v_lshl_add_u64 v[98:99], s[66:67], 0, v[96:97]
	s_mov_b64 s[26:27], 0x1800
	v_lshl_add_u64 v[100:101], v[176:177], 0, s[26:27]
	global_load_dwordx4 v[104:107], v[98:99], off
	global_load_dwordx4 v[108:111], v[100:101], off nt
	s_nop 0
	global_load_dwordx4 v[96:99], v[98:99], off offset:256
	s_nop 0
	global_load_dwordx4 v[100:103], v[100:101], off offset:1024 nt
	ds_read_b32 v128, v205 offset:128
	v_add_u32_e32 v130, s46, v154
	v_ashrrev_i32_e32 v131, 31, v130
	v_lshlrev_b64 v[130:131], 11, v[130:131]
	s_waitcnt lgkmcnt(0)
	v_pk_mul_f32 v[94:95], v[94:95], v[128:129] op_sel_hi:[1,0]
	v_pk_mul_f32 v[92:93], v[92:93], v[128:129] op_sel_hi:[1,0]
	v_pk_mul_f32 v[132:133], v[90:91], v[128:129] op_sel_hi:[1,0]
	v_pk_mul_f32 v[134:135], v[88:89], v[128:129] op_sel_hi:[1,0]
	v_mul_f32_e32 v88, 0xbfb8aa3b, v92
	v_mul_f32_e32 v89, 0xbfb8aa3b, v93
	v_mul_f32_e32 v92, 0xbfb8aa3b, v94
	v_mul_f32_e32 v93, 0xbfb8aa3b, v95
	v_exp_f32_e32 v88, v88
	v_exp_f32_e32 v89, v89
	v_exp_f32_e32 v92, v92
	v_exp_f32_e32 v93, v93
	v_add_f32_e32 v88, 1.0, v88
	v_add_f32_e32 v89, 1.0, v89
	v_rcp_f32_e32 v88, v88
	v_rcp_f32_e32 v89, v89
	v_add_f32_e32 v92, 1.0, v92
	v_add_f32_e32 v93, 1.0, v93
	v_rcp_f32_e32 v92, v92
	v_rcp_f32_e32 v93, v93
	v_pk_mul_f32 v[86:87], v[86:87], v[128:129] op_sel_hi:[1,0]
	v_pk_mul_f32 v[84:85], v[84:85], v[128:129] op_sel_hi:[1,0]
	v_mul_f32_e32 v86, 0xbfb8aa3b, v86
	v_mul_f32_e32 v84, 0xbfb8aa3b, v84
	v_mul_f32_e32 v85, 0xbfb8aa3b, v85
	v_mul_f32_e32 v87, 0xbfb8aa3b, v87
	v_pk_mul_f32 v[82:83], v[82:83], v[128:129] op_sel_hi:[1,0]
	v_pk_mul_f32 v[80:81], v[80:81], v[128:129] op_sel_hi:[1,0]
	v_exp_f32_e32 v84, v84
	v_exp_f32_e32 v85, v85
	v_exp_f32_e32 v86, v86
	v_exp_f32_e32 v87, v87
	v_mul_f32_e32 v80, 0xbfb8aa3b, v80
	v_mul_f32_e32 v81, 0xbfb8aa3b, v81
	v_mul_f32_e32 v82, 0xbfb8aa3b, v82
	v_mul_f32_e32 v83, 0xbfb8aa3b, v83
	v_exp_f32_e32 v80, v80
	v_exp_f32_e32 v81, v81
	v_exp_f32_e32 v82, v82
	v_exp_f32_e32 v83, v83
	v_add_f32_e32 v84, 1.0, v84
	v_add_f32_e32 v85, 1.0, v85
	v_add_f32_e32 v86, 1.0, v86
	v_add_f32_e32 v87, 1.0, v87
	v_rcp_f32_e32 v84, v84
	v_rcp_f32_e32 v85, v85
	v_rcp_f32_e32 v86, v86
	v_rcp_f32_e32 v87, v87
	v_add_f32_e32 v80, 1.0, v80
	v_add_f32_e32 v81, 1.0, v81
	v_add_f32_e32 v82, 1.0, v82
	v_add_f32_e32 v83, 1.0, v83
	v_rcp_f32_e32 v80, v80
	v_rcp_f32_e32 v81, v81
	v_rcp_f32_e32 v82, v82
	v_rcp_f32_e32 v83, v83
	s_waitcnt vmcnt(7)
	v_lshlrev_b32_e32 v136, 16, v120
	s_waitcnt vmcnt(6)
; __device__ __forceinline__ unsigned cvt_pk_bf16(float lo, float hi) { const f32x2 v = {lo, hi}; return __builtin_bit_cast(unsigned, __builtin_convertvector(v, bfx2_t)); }
; __device__ __forceinline__ float bflo(unsigned w) { return __uint_as_float(w << 16); }
; __device__ __forceinline__ float bfhi(unsigned w) { return __uint_as_float(w & 0xffff0000u); }
; __device__ __forceinline__ unsigned lo_pack4(float a, float b, float c, float d) { int p = __builtin_amdgcn_cvt_pk_fp8_f32(a * 512.0f, b * 512.0f, 0, false); return (unsigned)__builtin_amdgcn_cvt_pk_fp8_f32(c * 512.0f, d * 512.0f, p, true); }
;     template <int NM> __device__ __forceinline__ void round(const AccT& acc, const Unit& u, int ai, int m0, int wr, int wc, int fr, int fq) const {
;     ...
;                     const u32x4 p = pv[mm][bj];
;                     const f32x4 a0 = acc[ai][bj][m][0] * r, a1 = acc[ai][bj][m][1] * r;
;                     d0 = (f32x4){fsigmoid(a0[0]) * bflo(p.x), fsigmoid(a0[1]) * bfhi(p.x), fsigmoid(a0[2]) * bflo(p.y), fsigmoid(a0[3]) * bfhi(p.y)};
;                     d1 = (f32x4){fsigmoid(a1[0]) * bflo(p.z), fsigmoid(a1[1]) * bfhi(p.z), fsigmoid(a1[2]) * bflo(p.w), fsigmoid(a1[3]) * bfhi(p.w)};
;                 }
;                 const u32x4 H = hv[mm][bj]; const u32x2 L = lv[mm][bj];
;                 const f32x4 o0 = ((f32x4){bflo(H.x), bfhi(H.x), bflo(H.y), bfhi(H.y)} + lo_unpack4(L.x)) + d0;
;                 const f32x4 o1 = ((f32x4){bflo(H.z), bfhi(H.z), bflo(H.w), bfhi(H.w)} + lo_unpack4(L.y)) + d1;
;                 u32x4 w; w.x = cvt_pk_bf16(o0[0], o0[1]); w.y = cvt_pk_bf16(o0[2], o0[3]); w.z = cvt_pk_bf16(o1[0], o1[1]); w.w = cvt_pk_bf16(o1[2], o1[3]);
;                 u32x2 wl; wl.x = lo_pack4(o0[0] - bflo(w.x), o0[1] - bfhi(w.x), o0[2] - bflo(w.y), o0[3] - bfhi(w.y));
;                 wl.y = lo_pack4(o1[0] - bflo(w.z), o1[1] - bfhi(w.z), o1[2] - bflo(w.w), o1[3] - bfhi(w.w));
;                 *GP(u32x4, hout + off + bj * 128) = w; (void)wl;
;                 ss += (o0[0] * o0[0] + o0[1] * o0[1]) + (o0[2] * o0[2] + o0[3] * o0[3]) + (o1[0] * o1[0] + o1[1] * o1[1]) + (o1[2] * o1[2] + o1[3] * o1[3]);
;             }
;             ss += __shfl_xor(ss, 16); ss += __shfl_xor(ss, 32);
;             if (fq == 0) *GP(float, ssp + (size_t)(u.pn * 4 + wc) * TT + row) = ss;
	v_lshlrev_b32_e32 v90, 16, v124
	v_and_b32_e32 v91, 0xffff0000, v124
	v_lshlrev_b32_e32 v94, 16, v125
	v_and_b32_e32 v95, 0xffff0000, v125
	v_mul_f32_e32 v124, 0xbfb8aa3b, v134
	v_mul_f32_e32 v125, 0xbfb8aa3b, v135
	v_lshlrev_b32_e32 v134, 16, v126
	v_and_b32_e32 v135, 0xffff0000, v126
	v_mul_f32_e32 v126, 0xbfb8aa3b, v132
	v_exp_f32_e32 v126, v126
	v_exp_f32_e32 v124, v124
	v_exp_f32_e32 v125, v125
	v_and_b32_e32 v137, 0xffff0000, v120
	v_add_f32_e32 v126, 1.0, v126
	v_rcp_f32_e32 v132, v126
	v_mul_f32_e32 v126, 0xbfb8aa3b, v133
	v_exp_f32_e32 v126, v126
	v_add_f32_e32 v124, 1.0, v124
	v_add_f32_e32 v125, 1.0, v125
	v_rcp_f32_e32 v124, v124
	v_add_f32_e32 v126, 1.0, v126
	v_rcp_f32_e32 v125, v125
	v_rcp_f32_e32 v133, v126
	v_pk_add_f32 v[136:137], v[146:147], v[136:137]
	v_lshlrev_b32_e32 v120, 16, v121
	v_and_b32_e32 v121, 0xffff0000, v121
	v_pk_fma_f32 v[136:137], v[88:89], v[90:91], v[136:137]
	v_lshlrev_b32_e32 v88, 16, v122
	v_and_b32_e32 v89, 0xffff0000, v122
	v_lshlrev_b32_e32 v90, 16, v123
	v_and_b32_e32 v91, 0xffff0000, v123
	v_lshl_add_u64 v[122:123], s[14:15], 0, v[130:131]
	v_lshlrev_b32_e32 v126, 16, v127
	v_and_b32_e32 v127, 0xffff0000, v127
	v_pk_add_f32 v[120:121], v[144:145], v[120:121]
	v_pk_add_f32 v[90:91], v[144:145], v[90:91]
	v_pk_add_f32 v[88:89], v[146:147], v[88:89]
	v_lshl_add_u64 v[122:123], s[16:17], 1, v[122:123]
	v_pk_fma_f32 v[92:93], v[92:93], v[94:95], v[120:121]
	v_pk_fma_f32 v[94:95], v[124:125], v[134:135], v[88:89]
	v_pk_fma_f32 v[120:121], v[132:133], v[126:127], v[90:91]
	v_lshl_add_u64 v[122:123], v[122:123], 0, s[62:63]
	v_cvt_pk_bf16_f32 v88, v136, v137
	v_cvt_pk_bf16_f32 v89, v92, v93
	v_cvt_pk_bf16_f32 v90, v94, v95
	v_cvt_pk_bf16_f32 v91, v120, v121
	v_lshl_add_u64 v[122:123], v[122:123], 0, v[168:169]
	global_store_dwordx4 v[122:123], v[88:91], off
	s_nop 1
	v_mul_f32_e32 v88, v137, v137
	v_mul_f32_e32 v89, v93, v93
	v_fmac_f32_e32 v88, v136, v136
	v_fmac_f32_e32 v89, v92, v92
	v_add_f32_e32 v88, v88, v89
	v_mul_f32_e32 v89, v95, v95
	v_fmac_f32_e32 v89, v94, v94
	v_add_f32_e32 v88, v89, v88
	v_mul_f32_e32 v89, v121, v121
	v_fmac_f32_e32 v89, v120, v120
	v_add_f32_e32 v120, v89, v88
	s_waitcnt vmcnt(5)
	v_lshlrev_b32_e32 v88, 16, v116
	v_and_b32_e32 v89, 0xffff0000, v116
	v_lshlrev_b32_e32 v90, 16, v117
	v_and_b32_e32 v91, 0xffff0000, v117
	v_lshlrev_b32_e32 v116, 16, v112
	v_and_b32_e32 v117, 0xffff0000, v112
	v_lshlrev_b32_e32 v112, 16, v113
	v_and_b32_e32 v113, 0xffff0000, v113
	v_pk_add_f32 v[112:113], v[144:145], v[112:113]
	v_pk_add_f32 v[116:117], v[146:147], v[116:117]
	v_pk_fma_f32 v[86:87], v[86:87], v[90:91], v[112:113]
	v_pk_fma_f32 v[84:85], v[84:85], v[88:89], v[116:117]
	v_lshlrev_b32_e32 v88, 16, v114
	v_and_b32_e32 v89, 0xffff0000, v114
	v_lshlrev_b32_e32 v90, 16, v115
	v_and_b32_e32 v91, 0xffff0000, v115
	v_lshlrev_b32_e32 v92, 16, v118
	v_and_b32_e32 v93, 0xffff0000, v118
	v_lshlrev_b32_e32 v94, 16, v119
	v_and_b32_e32 v95, 0xffff0000, v119
	v_pk_add_f32 v[90:91], v[144:145], v[90:91]
	v_pk_add_f32 v[88:89], v[146:147], v[88:89]
	v_pk_fma_f32 v[90:91], v[82:83], v[94:95], v[90:91]
	v_pk_fma_f32 v[88:89], v[80:81], v[92:93], v[88:89]
	v_cvt_pk_bf16_f32 v80, v84, v85
	v_cvt_pk_bf16_f32 v81, v86, v87
	v_cvt_pk_bf16_f32 v82, v88, v89
	v_cvt_pk_bf16_f32 v83, v90, v91
	global_store_dwordx4 v[122:123], v[80:83], off offset:256
	s_nop 1
	v_mul_f32_e32 v80, v85, v85
	v_mul_f32_e32 v81, v87, v87
	v_fmac_f32_e32 v80, v84, v84
	v_fmac_f32_e32 v81, v86, v86
	v_add_f32_e32 v80, v80, v81
	v_mul_f32_e32 v81, v89, v89
	v_fmac_f32_e32 v81, v88, v88
	v_add_f32_e32 v80, v81, v80
	v_mul_f32_e32 v81, v91, v91
	v_fmac_f32_e32 v81, v90, v90
	v_add_f32_e32 v80, v81, v80
	v_add_f32_e32 v80, v120, v80
	v_mov_b32_e32 v81, v80
	s_nop 1
	v_permlane16_swap_b32_e32 v80, v81
	s_waitcnt lgkmcnt(0)
	v_add_f32_e32 v80, v80, v81
	v_mov_b32_e32 v81, v80
	s_nop 1
	v_permlane32_swap_b32_e32 v80, v81
	s_and_saveexec_b64 s[12:13], s[42:43]
	s_cbranch_execz .LBB0_583
	s_lshl_b32 s20, s25, 2
	s_or_b32 s20, s20, s71
	s_ashr_i32 s21, s20, 31
	s_lshl_b64 s[20:21], s[20:21], 18
	s_add_u32 s20, s65, s20
	s_addc_u32 s21, s70, s21
	s_ashr_i32 s47, s46, 31
	s_waitcnt lgkmcnt(0)
	v_add_f32_e32 v82, v80, v81
	v_lshl_add_u64 v[80:81], s[46:47], 0, v[148:149]
	v_lshl_add_u64 v[80:81], v[80:81], 2, s[20:21]
	global_store_dword v[80:81], v82, off offset:128

;     template <int NM> __device__ __forceinline__ void round(const AccT& acc, const Unit& u, int ai, int m0, int wr, int wc, int fr, int fq) const {
;         u32x4 hv[NM][2], pv[NM][2]; u32x2 lv[NM][2];
; #pragma unroll
;         for (int mm = 0; mm < NM; ++mm) {
;             const int rl = ai * 128 + wr * 64 + (m0 + mm) * 16 + fr;
;             const size_t off = (size_t)(u.pm * 256 + rl) * DM + u.pn * 256 + wc * 32 + 8 * fq;
; #pragma unroll
;             for (int bj = 0; bj < 2; ++bj) {
;                 hv[mm][bj] = *GP(const u32x4, hin + off + bj * 128); lv[mm][bj] = (u32x2){0u, 0u};
;                 if (MODE == 1) pv[mm][bj] = *GP(const u32x4, proj + off + bj * 128);
;             }
;         }
; #pragma unroll
;         for (int mm = 0; mm < NM; ++mm) {
;             const int m = m0 + mm;
;             const int rl = ai * 128 + wr * 64 + m * 16 + fr; const int row = u.pm * 256 + rl;
;             const size_t off = (size_t)row * DM + u.pn * 256 + wc * 32 + 8 * fq;
;             float r = 1.f; if (MODE == 1) r = rs[((u.pm >> 3) & 3) * 256 + rl];
;             float ss = 0.f;
; #pragma unroll
;             for (int bj = 0; bj < 2; ++bj) {
;                 f32x4 d0, d1;
;                 if (MODE == 0) { d0 = acc[ai][bj][m][0] * alpha; d1 = acc[ai][bj][m][1] * alpha; }
;                 else {
;                     const u32x4 p = pv[mm][bj];
;                     const f32x4 a0 = acc[ai][bj][m][0] * r, a1 = acc[ai][bj][m][1] * r;
;                     d0 = (f32x4){fsigmoid(a0[0]) * bflo(p.x), fsigmoid(a0[1]) * bfhi(p.x), fsigmoid(a0[2]) * bflo(p.y), fsigmoid(a0[3]) * bfhi(p.y)};
;                     d1 = (f32x4){fsigmoid(a1[0]) * bflo(p.z), fsigmoid(a1[1]) * bfhi(p.z), fsigmoid(a1[2]) * bflo(p.w), fsigmoid(a1[3]) * bfhi(p.w)};
;                 }
;                 const u32x4 H = hv[mm][bj]; const u32x2 L = lv[mm][bj];
;                 const f32x4 o0 = ((f32x4){bflo(H.x), bfhi(H.x), bflo(H.y), bfhi(H.y)} + lo_unpack4(L.x)) + d0;
;                 const f32x4 o1 = ((f32x4){bflo(H.z), bfhi(H.z), bflo(H.w), bfhi(H.w)} + lo_unpack4(L.y)) + d1;
;                 u32x4 w; w.x = cvt_pk_bf16(o0[0], o0[1]); w.y = cvt_pk_bf16(o0[2], o0[3]); w.z = cvt_pk_bf16(o1[0], o1[1]); w.w = cvt_pk_bf16(o1[2], o1[3]);
;                 u32x2 wl; wl.x = lo_pack4(o0[0] - bflo(w.x), o0[1] - bfhi(w.x), o0[2] - bflo(w.y), o0[3] - bfhi(w.y));
.LBB0_585:
	s_or_b64 exec, exec, s[12:13]
	v_add_u32_e32 v88, s46, v198
	v_ashrrev_i32_e32 v89, 31, v88
	s_waitcnt lgkmcnt(0)
	v_lshlrev_b64 v[64:65], 10, v[88:89]
	v_lshl_add_u64 v[64:65], v[64:65], 0, v[158:159]
	v_lshlrev_b64 v[64:65], 1, v[64:65]
	v_lshl_add_u64 v[66:67], s[66:67], 0, v[64:65]
	s_mov_b64 s[26:27], 0x2000
	v_lshl_add_u64 v[64:65], v[176:177], 0, s[26:27]
	global_load_dwordx4 v[92:95], v[66:67], off
	global_load_dwordx4 v[98:101], v[64:65], off nt
	global_load_dwordx4 v[80:83], v[66:67], off offset:256
	global_load_dwordx4 v[84:87], v[64:65], off offset:1024 nt
	v_or_b32_e32 v64, 16, v88
	v_ashrrev_i32_e32 v65, 31, v64
	v_lshlrev_b64 v[64:65], 10, v[64:65]
	v_lshl_add_u64 v[64:65], v[64:65], 0, v[158:159]
	v_lshlrev_b64 v[64:65], 1, v[64:65]
	v_lshl_add_u64 v[66:67], s[66:67], 0, v[64:65]
	s_mov_b64 s[26:27], 0x2800
	v_lshl_add_u64 v[68:69], v[176:177], 0, s[26:27]
	global_load_dwordx4 v[72:75], v[66:67], off
	global_load_dwordx4 v[76:79], v[68:69], off nt
	s_nop 0
	global_load_dwordx4 v[64:67], v[66:67], off offset:256
	s_nop 0
	global_load_dwordx4 v[68:71], v[68:69], off offset:1024 nt
	ds_read_b32 v90, v205 offset:512
	v_lshlrev_b64 v[96:97], 11, v[88:89]
	v_lshl_add_u64 v[96:97], s[14:15], 0, v[96:97]
	v_lshl_add_u64 v[96:97], s[16:17], 1, v[96:97]
	v_lshl_add_u64 v[96:97], v[96:97], 0, s[62:63]
	s_waitcnt lgkmcnt(0)
	v_pk_mul_f32 v[62:63], v[62:63], v[90:91] op_sel_hi:[1,0]
	v_pk_mul_f32 v[60:61], v[60:61], v[90:91] op_sel_hi:[1,0]
	v_mul_f32_e32 v62, 0xbfb8aa3b, v62
	v_mul_f32_e32 v60, 0xbfb8aa3b, v60
	v_mul_f32_e32 v61, 0xbfb8aa3b, v61
	v_mul_f32_e32 v63, 0xbfb8aa3b, v63
	v_pk_mul_f32 v[58:59], v[58:59], v[90:91] op_sel_hi:[1,0]
	v_pk_mul_f32 v[56:57], v[56:57], v[90:91] op_sel_hi:[1,0]
	v_exp_f32_e32 v60, v60
	v_exp_f32_e32 v61, v61
	v_exp_f32_e32 v62, v62
	v_exp_f32_e32 v63, v63
	v_mul_f32_e32 v56, 0xbfb8aa3b, v56
	v_mul_f32_e32 v57, 0xbfb8aa3b, v57
	v_mul_f32_e32 v58, 0xbfb8aa3b, v58
	v_mul_f32_e32 v59, 0xbfb8aa3b, v59
	v_exp_f32_e32 v56, v56
	v_exp_f32_e32 v57, v57
	v_exp_f32_e32 v58, v58
	v_exp_f32_e32 v59, v59
	v_add_f32_e32 v60, 1.0, v60
	v_add_f32_e32 v61, 1.0, v61
	v_add_f32_e32 v62, 1.0, v62
	v_add_f32_e32 v63, 1.0, v63
	v_rcp_f32_e32 v60, v60
	v_rcp_f32_e32 v61, v61
	v_rcp_f32_e32 v62, v62
	v_rcp_f32_e32 v63, v63
	v_add_f32_e32 v56, 1.0, v56
	v_add_f32_e32 v57, 1.0, v57
	v_add_f32_e32 v58, 1.0, v58
	v_add_f32_e32 v59, 1.0, v59
	v_rcp_f32_e32 v56, v56
	v_rcp_f32_e32 v57, v57
	v_rcp_f32_e32 v58, v58
	v_rcp_f32_e32 v59, v59
	v_lshl_add_u64 v[96:97], v[96:97], 0, v[168:169]
	s_waitcnt vmcnt(7)
	v_lshlrev_b32_e32 v106, 16, v92
	v_and_b32_e32 v107, 0xffff0000, v92
	v_lshlrev_b32_e32 v92, 16, v93
	v_and_b32_e32 v93, 0xffff0000, v93
	s_waitcnt vmcnt(6)
	v_lshlrev_b32_e32 v102, 16, v98
	v_and_b32_e32 v103, 0xffff0000, v98
	v_lshlrev_b32_e32 v98, 16, v99
	v_and_b32_e32 v99, 0xffff0000, v99
	v_pk_add_f32 v[108:109], v[144:145], v[92:93]
	v_pk_add_f32 v[92:93], v[146:147], v[106:107]
	v_lshlrev_b32_e32 v104, 16, v100
	v_pk_fma_f32 v[92:93], v[60:61], v[102:103], v[92:93]
	v_pk_fma_f32 v[60:61], v[62:63], v[98:99], v[108:109]
	v_lshlrev_b32_e32 v62, 16, v94
	v_and_b32_e32 v63, 0xffff0000, v94
	v_lshlrev_b32_e32 v94, 16, v95
	v_and_b32_e32 v95, 0xffff0000, v95
	v_and_b32_e32 v105, 0xffff0000, v100
	v_lshlrev_b32_e32 v100, 16, v101
	v_and_b32_e32 v101, 0xffff0000, v101
	v_pk_add_f32 v[98:99], v[144:145], v[94:95]
	v_pk_add_f32 v[62:63], v[146:147], v[62:63]
	s_nop 0
	v_pk_fma_f32 v[94:95], v[56:57], v[104:105], v[62:63]
	v_pk_fma_f32 v[62:63], v[58:59], v[100:101], v[98:99]
	v_cvt_pk_bf16_f32 v56, v92, v93
	v_cvt_pk_bf16_f32 v57, v60, v61
	v_cvt_pk_bf16_f32 v58, v94, v95
	v_cvt_pk_bf16_f32 v59, v62, v63
	global_store_dwordx4 v[96:97], v[56:59], off
	s_nop 1
	v_mul_f32_e32 v56, v93, v93
	v_mul_f32_e32 v57, v61, v61
	v_fmac_f32_e32 v56, v92, v92
	v_fmac_f32_e32 v57, v60, v60
	v_add_f32_e32 v56, v56, v57
	v_mul_f32_e32 v57, v95, v95
	v_fmac_f32_e32 v57, v94, v94
	v_add_f32_e32 v56, v57, v56
	v_mul_f32_e32 v57, v63, v63
	v_fmac_f32_e32 v57, v62, v62
	v_add_f32_e32 v91, v57, v56
	v_pk_mul_f32 v[54:55], v[54:55], v[90:91] op_sel_hi:[1,0]
	v_pk_mul_f32 v[52:53], v[52:53], v[90:91] op_sel_hi:[1,0]
	v_mul_f32_e32 v54, 0xbfb8aa3b, v54
	v_mul_f32_e32 v52, 0xbfb8aa3b, v52
	v_mul_f32_e32 v53, 0xbfb8aa3b, v53
	v_mul_f32_e32 v55, 0xbfb8aa3b, v55
	v_pk_mul_f32 v[50:51], v[50:51], v[90:91] op_sel_hi:[1,0]
	v_pk_mul_f32 v[48:49], v[48:49], v[90:91] op_sel_hi:[1,0]
	v_exp_f32_e32 v52, v52
	v_exp_f32_e32 v53, v53
	v_exp_f32_e32 v54, v54
	v_exp_f32_e32 v55, v55
	v_mul_f32_e32 v48, 0xbfb8aa3b, v48
	v_mul_f32_e32 v49, 0xbfb8aa3b, v49
	v_mul_f32_e32 v50, 0xbfb8aa3b, v50
	v_mul_f32_e32 v51, 0xbfb8aa3b, v51
	v_exp_f32_e32 v48, v48
	v_exp_f32_e32 v49, v49
	v_exp_f32_e32 v50, v50
	v_exp_f32_e32 v51, v51
	v_add_f32_e32 v52, 1.0, v52
	v_add_f32_e32 v53, 1.0, v53
	v_add_f32_e32 v54, 1.0, v54
	v_add_f32_e32 v55, 1.0, v55
	v_rcp_f32_e32 v52, v52
	v_rcp_f32_e32 v53, v53
	v_rcp_f32_e32 v54, v54
	v_rcp_f32_e32 v55, v55
	v_add_f32_e32 v48, 1.0, v48
	v_add_f32_e32 v49, 1.0, v49
	v_add_f32_e32 v50, 1.0, v50
	v_add_f32_e32 v51, 1.0, v51
	s_waitcnt vmcnt(5)
	v_lshlrev_b32_e32 v56, 16, v84
	v_and_b32_e32 v57, 0xffff0000, v84
	v_lshlrev_b32_e32 v58, 16, v85
	v_and_b32_e32 v59, 0xffff0000, v85
	v_rcp_f32_e32 v48, v48
	v_rcp_f32_e32 v49, v49
	v_rcp_f32_e32 v50, v50
	v_rcp_f32_e32 v51, v51
	v_lshlrev_b32_e32 v84, 16, v80
	v_and_b32_e32 v85, 0xffff0000, v80
	v_lshlrev_b32_e32 v80, 16, v81
	v_and_b32_e32 v81, 0xffff0000, v81
	v_pk_add_f32 v[80:81], v[144:145], v[80:81]
	v_pk_add_f32 v[84:85], v[146:147], v[84:85]
	v_pk_fma_f32 v[54:55], v[54:55], v[58:59], v[80:81]
	v_pk_fma_f32 v[52:53], v[52:53], v[56:57], v[84:85]
	v_lshlrev_b32_e32 v56, 16, v82
	v_and_b32_e32 v57, 0xffff0000, v82
	v_lshlrev_b32_e32 v58, 16, v83
	v_and_b32_e32 v59, 0xffff0000, v83
	v_lshlrev_b32_e32 v60, 16, v86
	v_and_b32_e32 v61, 0xffff0000, v86
	v_lshlrev_b32_e32 v62, 16, v87
	v_and_b32_e32 v63, 0xffff0000, v87
	v_pk_add_f32 v[58:59], v[144:145], v[58:59]
	v_pk_add_f32 v[56:57], v[146:147], v[56:57]
	v_pk_fma_f32 v[58:59], v[50:51], v[62:63], v[58:59]
	v_pk_fma_f32 v[56:57], v[48:49], v[60:61], v[56:57]
	v_cvt_pk_bf16_f32 v48, v52, v53
	v_cvt_pk_bf16_f32 v49, v54, v55
	v_cvt_pk_bf16_f32 v50, v56, v57
	v_cvt_pk_bf16_f32 v51, v58, v59
	global_store_dwordx4 v[96:97], v[48:51], off offset:256
	s_nop 1
	v_mul_f32_e32 v48, v53, v53
	v_mul_f32_e32 v49, v55, v55
	v_fmac_f32_e32 v48, v52, v52
	v_fmac_f32_e32 v49, v54, v54
	v_add_f32_e32 v48, v48, v49
	v_mul_f32_e32 v49, v57, v57
	v_fmac_f32_e32 v49, v56, v56
	v_add_f32_e32 v48, v49, v48
	v_mul_f32_e32 v49, v59, v59
	v_fmac_f32_e32 v49, v58, v58
	v_add_f32_e32 v48, v49, v48
	v_add_f32_e32 v48, v91, v48
	v_mov_b32_e32 v49, v48
	s_nop 1
	v_permlane16_swap_b32_e32 v48, v49
	s_waitcnt lgkmcnt(0)
	v_add_f32_e32 v48, v48, v49
	v_mov_b32_e32 v49, v48
	s_nop 1
	v_permlane32_swap_b32_e32 v48, v49
	s_and_saveexec_b64 s[12:13], s[42:43]
	s_cbranch_execz .LBB0_587
;     template <int NM> __device__ __forceinline__ void round(const AccT& acc, const Unit& u, int ai, int m0, int wr, int wc, int fr, int fq) const {
;     ...
;             ss += __shfl_xor(ss, 16); ss += __shfl_xor(ss, 32);
;             if (fq == 0) *GP(float, ssp + (size_t)(u.pn * 4 + wc) * TT + row) = ss;
	s_lshl_b32 s20, s25, 2
	s_or_b32 s20, s20, s71
	s_ashr_i32 s21, s20, 31
	s_lshl_b64 s[20:21], s[20:21], 18
	s_add_u32 s20, s65, s20
	s_addc_u32 s21, s70, s21
	s_waitcnt lgkmcnt(0)
	v_add_f32_e32 v50, v48, v49
	v_lshl_add_u64 v[48:49], v[88:89], 2, s[20:21]
	global_store_dword v[48:49], v50, off

;     template <int NM> __device__ __forceinline__ void round(const AccT& acc, const Unit& u, int ai, int m0, int wr, int wc, int fr, int fq) const {
;         u32x4 hv[NM][2], pv[NM][2]; u32x2 lv[NM][2];
; #pragma unroll
;         for (int mm = 0; mm < NM; ++mm) {
;             const int rl = ai * 128 + wr * 64 + (m0 + mm) * 16 + fr;
;             const size_t off = (size_t)(u.pm * 256 + rl) * DM + u.pn * 256 + wc * 32 + 8 * fq;
; #pragma unroll
;             for (int bj = 0; bj < 2; ++bj) {
;                 hv[mm][bj] = *GP(const u32x4, hin + off + bj * 128); lv[mm][bj] = (u32x2){0u, 0u};
;                 if (MODE == 1) pv[mm][bj] = *GP(const u32x4, proj + off + bj * 128);
;             }
;         }
; #pragma unroll
;         for (int mm = 0; mm < NM; ++mm) {
;             const int m = m0 + mm;
;             const int rl = ai * 128 + wr * 64 + m * 16 + fr; const int row = u.pm * 256 + rl;
;             const size_t off = (size_t)row * DM + u.pn * 256 + wc * 32 + 8 * fq;
;             float r = 1.f; if (MODE == 1) r = rs[((u.pm >> 3) & 3) * 256 + rl];
;             float ss = 0.f;
; #pragma unroll
;             for (int bj = 0; bj < 2; ++bj) {
;                 f32x4 d0, d1;
;                 if (MODE == 0) { d0 = acc[ai][bj][m][0] * alpha; d1 = acc[ai][bj][m][1] * alpha; }
;                 else {
;                     const u32x4 p = pv[mm][bj];
;                     const f32x4 a0 = acc[ai][bj][m][0] * r, a1 = acc[ai][bj][m][1] * r;
;                     d0 = (f32x4){fsigmoid(a0[0]) * bflo(p.x), fsigmoid(a0[1]) * bfhi(p.x), fsigmoid(a0[2]) * bflo(p.y), fsigmoid(a0[3]) * bfhi(p.y)};
;                     d1 = (f32x4){fsigmoid(a1[0]) * bflo(p.z), fsigmoid(a1[1]) * bfhi(p.z), fsigmoid(a1[2]) * bflo(p.w), fsigmoid(a1[3]) * bfhi(p.w)};
;                 }
;                 const u32x4 H = hv[mm][bj]; const u32x2 L = lv[mm][bj];
;                 const f32x4 o0 = ((f32x4){bflo(H.x), bfhi(H.x), bflo(H.y), bfhi(H.y)} + lo_unpack4(L.x)) + d0;
;                 const f32x4 o1 = ((f32x4){bflo(H.z), bfhi(H.z), bflo(H.w), bfhi(H.w)} + lo_unpack4(L.y)) + d1;
;                 u32x4 w; w.x = cvt_pk_bf16(o0[0], o0[1]); w.y = cvt_pk_bf16(o0[2], o0[3]); w.z = cvt_pk_bf16(o1[0], o1[1]); w.w = cvt_pk_bf16(o1[2], o1[3]);
;                 u32x2 wl; wl.x = lo_pack4(o0[0] - bflo(w.x), o0[1] - bfhi(w.x), o0[2] - bflo(w.y), o0[3] - bfhi(w.y));
.LBB0_589:
	s_or_b64 exec, exec, s[12:13]
	v_or_b32_e32 v32, 32, v88
	s_waitcnt lgkmcnt(0)
	v_ashrrev_i32_e32 v33, 31, v32
	v_lshlrev_b64 v[32:33], 10, v[32:33]
	v_lshl_add_u64 v[32:33], v[32:33], 0, v[158:159]
	v_lshlrev_b64 v[32:33], 1, v[32:33]
	v_lshl_add_u64 v[34:35], s[66:67], 0, v[32:33]
	s_mov_b64 s[26:27], 0x3000
	v_lshl_add_u64 v[32:33], v[176:177], 0, s[26:27]
	global_load_dwordx4 v[56:59], v[34:35], off
	global_load_dwordx4 v[60:63], v[32:33], off nt
	global_load_dwordx4 v[48:51], v[34:35], off offset:256
	global_load_dwordx4 v[52:55], v[32:33], off offset:1024 nt
	v_or_b32_e32 v32, 48, v88
	v_ashrrev_i32_e32 v33, 31, v32
	v_lshlrev_b64 v[32:33], 10, v[32:33]
	v_lshl_add_u64 v[32:33], v[32:33], 0, v[158:159]
	v_lshlrev_b64 v[32:33], 1, v[32:33]
	v_lshl_add_u64 v[34:35], s[66:67], 0, v[32:33]
	s_mov_b64 s[26:27], 0x3800
	v_lshl_add_u64 v[36:37], v[176:177], 0, s[26:27]
	global_load_dwordx4 v[40:43], v[34:35], off
	global_load_dwordx4 v[44:47], v[36:37], off nt
	s_nop 0
	global_load_dwordx4 v[32:35], v[34:35], off offset:256
	s_nop 0
	global_load_dwordx4 v[36:39], v[36:37], off offset:1024 nt
	ds_read_b32 v64, v205 offset:640
	v_add_u32_e32 v66, s46, v200
	v_ashrrev_i32_e32 v67, 31, v66
	v_lshlrev_b64 v[66:67], 11, v[66:67]
	s_waitcnt lgkmcnt(0)
	v_pk_mul_f32 v[30:31], v[30:31], v[64:65] op_sel_hi:[1,0]
	v_pk_mul_f32 v[28:29], v[28:29], v[64:65] op_sel_hi:[1,0]
	v_pk_mul_f32 v[68:69], v[26:27], v[64:65] op_sel_hi:[1,0]
	v_pk_mul_f32 v[70:71], v[24:25], v[64:65] op_sel_hi:[1,0]
	v_mul_f32_e32 v24, 0xbfb8aa3b, v28
	v_mul_f32_e32 v25, 0xbfb8aa3b, v29
	v_mul_f32_e32 v28, 0xbfb8aa3b, v30
	v_mul_f32_e32 v29, 0xbfb8aa3b, v31
	v_exp_f32_e32 v24, v24
	v_exp_f32_e32 v25, v25
	v_exp_f32_e32 v28, v28
	v_exp_f32_e32 v29, v29
	v_add_f32_e32 v24, 1.0, v24
	v_add_f32_e32 v25, 1.0, v25
	v_rcp_f32_e32 v24, v24
	v_rcp_f32_e32 v25, v25
	v_add_f32_e32 v28, 1.0, v28
	v_add_f32_e32 v29, 1.0, v29
	v_rcp_f32_e32 v28, v28
	v_rcp_f32_e32 v29, v29
	v_pk_mul_f32 v[22:23], v[22:23], v[64:65] op_sel_hi:[1,0]
	v_pk_mul_f32 v[20:21], v[20:21], v[64:65] op_sel_hi:[1,0]
	v_mul_f32_e32 v22, 0xbfb8aa3b, v22
	v_mul_f32_e32 v20, 0xbfb8aa3b, v20
	v_mul_f32_e32 v21, 0xbfb8aa3b, v21
	v_mul_f32_e32 v23, 0xbfb8aa3b, v23
	v_pk_mul_f32 v[18:19], v[18:19], v[64:65] op_sel_hi:[1,0]
	v_pk_mul_f32 v[16:17], v[16:17], v[64:65] op_sel_hi:[1,0]
	v_exp_f32_e32 v20, v20
	v_exp_f32_e32 v21, v21
	v_exp_f32_e32 v22, v22
	v_exp_f32_e32 v23, v23
	v_mul_f32_e32 v16, 0xbfb8aa3b, v16
	v_mul_f32_e32 v17, 0xbfb8aa3b, v17
	v_mul_f32_e32 v18, 0xbfb8aa3b, v18
	v_mul_f32_e32 v19, 0xbfb8aa3b, v19
	v_exp_f32_e32 v16, v16
	v_exp_f32_e32 v17, v17
	v_exp_f32_e32 v18, v18
	v_exp_f32_e32 v19, v19
	v_add_f32_e32 v20, 1.0, v20
	v_add_f32_e32 v21, 1.0, v21
	v_add_f32_e32 v22, 1.0, v22
	v_add_f32_e32 v23, 1.0, v23
	v_rcp_f32_e32 v20, v20
	v_rcp_f32_e32 v21, v21
	v_rcp_f32_e32 v22, v22
	v_rcp_f32_e32 v23, v23
	v_add_f32_e32 v16, 1.0, v16
	v_add_f32_e32 v17, 1.0, v17
	v_add_f32_e32 v18, 1.0, v18
	v_add_f32_e32 v19, 1.0, v19
	v_rcp_f32_e32 v16, v16
	v_rcp_f32_e32 v17, v17
	v_rcp_f32_e32 v18, v18
	v_rcp_f32_e32 v19, v19
	s_waitcnt vmcnt(7)
	v_lshlrev_b32_e32 v72, 16, v56
	s_waitcnt vmcnt(6)
	v_lshlrev_b32_e32 v26, 16, v60
	v_and_b32_e32 v27, 0xffff0000, v60
	v_lshlrev_b32_e32 v30, 16, v61
	v_and_b32_e32 v31, 0xffff0000, v61
	v_mul_f32_e32 v60, 0xbfb8aa3b, v70
	v_mul_f32_e32 v61, 0xbfb8aa3b, v71
	v_lshlrev_b32_e32 v70, 16, v62
	v_and_b32_e32 v71, 0xffff0000, v62
	v_mul_f32_e32 v62, 0xbfb8aa3b, v68
	v_exp_f32_e32 v62, v62
	v_exp_f32_e32 v60, v60
	v_exp_f32_e32 v61, v61
	v_and_b32_e32 v73, 0xffff0000, v56
	v_add_f32_e32 v62, 1.0, v62
	v_rcp_f32_e32 v68, v62
	v_mul_f32_e32 v62, 0xbfb8aa3b, v69
	v_exp_f32_e32 v62, v62
	v_add_f32_e32 v60, 1.0, v60
	v_add_f32_e32 v61, 1.0, v61
	v_rcp_f32_e32 v60, v60
	v_add_f32_e32 v62, 1.0, v62
	v_rcp_f32_e32 v61, v61
	v_rcp_f32_e32 v69, v62
	v_pk_add_f32 v[72:73], v[146:147], v[72:73]
	v_lshlrev_b32_e32 v56, 16, v57
	v_and_b32_e32 v57, 0xffff0000, v57
	v_pk_fma_f32 v[72:73], v[24:25], v[26:27], v[72:73]
	v_lshlrev_b32_e32 v24, 16, v58
	v_and_b32_e32 v25, 0xffff0000, v58
	v_lshlrev_b32_e32 v26, 16, v59
	v_and_b32_e32 v27, 0xffff0000, v59
	v_lshl_add_u64 v[58:59], s[14:15], 0, v[66:67]
	v_lshlrev_b32_e32 v62, 16, v63
	v_and_b32_e32 v63, 0xffff0000, v63
	v_pk_add_f32 v[56:57], v[144:145], v[56:57]
	v_pk_add_f32 v[26:27], v[144:145], v[26:27]
	v_pk_add_f32 v[24:25], v[146:147], v[24:25]
	v_lshl_add_u64 v[58:59], s[16:17], 1, v[58:59]
	v_pk_fma_f32 v[28:29], v[28:29], v[30:31], v[56:57]
	v_pk_fma_f32 v[30:31], v[60:61], v[70:71], v[24:25]
	v_pk_fma_f32 v[56:57], v[68:69], v[62:63], v[26:27]
	v_lshl_add_u64 v[58:59], v[58:59], 0, s[62:63]
	v_cvt_pk_bf16_f32 v24, v72, v73
	v_cvt_pk_bf16_f32 v25, v28, v29
	v_cvt_pk_bf16_f32 v26, v30, v31
	v_cvt_pk_bf16_f32 v27, v56, v57
	v_lshl_add_u64 v[58:59], v[58:59], 0, v[168:169]
	global_store_dwordx4 v[58:59], v[24:27], off
	s_nop 1
	v_mul_f32_e32 v24, v73, v73
	v_mul_f32_e32 v25, v29, v29
	v_fmac_f32_e32 v24, v72, v72
	v_fmac_f32_e32 v25, v28, v28
	v_add_f32_e32 v24, v24, v25
	v_mul_f32_e32 v25, v31, v31
	v_fmac_f32_e32 v25, v30, v30
	v_add_f32_e32 v24, v25, v24
	v_mul_f32_e32 v25, v57, v57
	v_fmac_f32_e32 v25, v56, v56
	v_add_f32_e32 v56, v25, v24
	s_waitcnt vmcnt(5)
	v_lshlrev_b32_e32 v24, 16, v52
	v_and_b32_e32 v25, 0xffff0000, v52
	v_lshlrev_b32_e32 v26, 16, v53
	v_and_b32_e32 v27, 0xffff0000, v53
	v_lshlrev_b32_e32 v52, 16, v48
	v_and_b32_e32 v53, 0xffff0000, v48
	v_lshlrev_b32_e32 v48, 16, v49
	v_and_b32_e32 v49, 0xffff0000, v49
	v_pk_add_f32 v[48:49], v[144:145], v[48:49]
	v_pk_add_f32 v[52:53], v[146:147], v[52:53]
	v_pk_fma_f32 v[22:23], v[22:23], v[26:27], v[48:49]
	v_pk_fma_f32 v[20:21], v[20:21], v[24:25], v[52:53]
	v_lshlrev_b32_e32 v24, 16, v50
	v_and_b32_e32 v25, 0xffff0000, v50
	v_lshlrev_b32_e32 v26, 16, v51
	v_and_b32_e32 v27, 0xffff0000, v51
	v_lshlrev_b32_e32 v28, 16, v54
	v_and_b32_e32 v29, 0xffff0000, v54
	v_lshlrev_b32_e32 v30, 16, v55
	v_and_b32_e32 v31, 0xffff0000, v55
	v_pk_add_f32 v[26:27], v[144:145], v[26:27]
	v_pk_add_f32 v[24:25], v[146:147], v[24:25]
	v_pk_fma_f32 v[26:27], v[18:19], v[30:31], v[26:27]
	v_pk_fma_f32 v[24:25], v[16:17], v[28:29], v[24:25]
	v_cvt_pk_bf16_f32 v16, v20, v21
	v_cvt_pk_bf16_f32 v17, v22, v23
	v_cvt_pk_bf16_f32 v18, v24, v25
	v_cvt_pk_bf16_f32 v19, v26, v27
	global_store_dwordx4 v[58:59], v[16:19], off offset:256
	s_nop 1
	v_mul_f32_e32 v16, v21, v21
	v_mul_f32_e32 v17, v23, v23
	v_fmac_f32_e32 v16, v20, v20
	v_fmac_f32_e32 v17, v22, v22
	v_add_f32_e32 v16, v16, v17
	v_mul_f32_e32 v17, v25, v25
	v_fmac_f32_e32 v17, v24, v24
	v_add_f32_e32 v16, v17, v16
	v_mul_f32_e32 v17, v27, v27
	v_fmac_f32_e32 v17, v26, v26
	v_add_f32_e32 v16, v17, v16
	v_add_f32_e32 v16, v56, v16
	v_mov_b32_e32 v17, v16
	s_nop 1
	v_permlane16_swap_b32_e32 v16, v17
	s_waitcnt lgkmcnt(0)
	v_add_f32_e32 v16, v16, v17
	v_mov_b32_e32 v17, v16
	s_nop 1
	v_permlane32_swap_b32_e32 v16, v17
	s_and_saveexec_b64 s[12:13], s[42:43]
	s_cbranch_execz .LBB0_591
;     template <int NM> __device__ __forceinline__ void round(const AccT& acc, const Unit& u, int ai, int m0, int wr, int wc, int fr, int fq) const {
;     ...
;             ss += __shfl_xor(ss, 16); ss += __shfl_xor(ss, 32);
;             if (fq == 0) *GP(float, ssp + (size_t)(u.pn * 4 + wc) * TT + row) = ss;
	s_lshl_b32 s20, s25, 2
	s_or_b32 s20, s20, s71
	s_ashr_i32 s21, s20, 31
	s_lshl_b64 s[20:21], s[20:21], 18
	s_add_u32 s20, s65, s20
	s_addc_u32 s21, s70, s21
	s_ashr_i32 s47, s46, 31
	s_waitcnt lgkmcnt(0)
	v_add_f32_e32 v18, v16, v17
	v_lshl_add_u64 v[16:17], s[46:47], 0, v[154:155]
	v_lshl_add_u64 v[16:17], v[16:17], 2, s[20:21]
	global_store_dword v[16:17], v18, off offset:512

; __device__ __forceinline__ float bflo(unsigned w) { return __uint_as_float(w << 16); }
; __device__ __forceinline__ float bfhi(unsigned w) { return __uint_as_float(w & 0xffff0000u); }
; __device__ __forceinline__ f32x4 lo_unpack4(unsigned w) { const f32x2 a = __builtin_amdgcn_cvt_pk_f32_fp8((int)w, false), b = __builtin_amdgcn_cvt_pk_f32_fp8((int)w, true); return (f32x4){a.x, a.y, b.x, b.y} * (1.0f / 512.0f); }
; __device__ void final_norm(const Params& P, const float* ssp, const bf16_t* hi, const unsigned char* lo) {
;     ...
;     for (int row = blockIdx.x * 8 + wave; row < TT; row += G * 8) {
;         float ss = (lane < 16) ? ssp[(size_t)lane * TT + row] : 0.f;
;         u32x2 hv[4]; unsigned lv[4];
; #pragma unroll
;         for (int q = 0; q < 4; ++q) { hv[q] = *(const u32x2*)(hi + (size_t)row * DM + q * 256 + lane * 4); lv[q] = 0u; }
; #pragma unroll
;         for (int o = 32; o >= 1; o >>= 1) ss += __shfl_xor(ss, o);
;         const float r = 1.0f / sqrtf(ss * (1.0f / 1024.0f) + 1e-6f);
; #pragma unroll
;         for (int q = 0; q < 4; ++q) { const f32x4 v = (f32x4){bflo(hv[q].x), bfhi(hv[q].x), bflo(hv[q].y), bfhi(hv[q].y)} + lo_unpack4(lv[q]);
;             *(f32x4*)(out + (size_t)row * DM + q * 256 + lane * 4) = v * r * w[q]; }
;     }
.LBB0_671:
	s_or_b64 exec, exec, s[2:3]
	global_load_dwordx2 v[42:43], v[24:25], off offset:-1024
	global_load_dwordx2 v[44:45], v[24:25], off offset:-512
	global_load_dwordx2 v[46:47], v[24:25], off
	global_load_dwordx2 v[48:49], v[24:25], off offset:512
	s_waitcnt vmcnt(0)
	v_mov_b32_e32 v41, v40
	s_nop 1
	v_permlane32_swap_b32_e32 v40, v41
	v_add_u32_e32 v160, v160, v164
	v_lshl_add_u64 v[20:21], v[20:21], 0, v[22:23]
	v_lshl_add_u64 v[24:25], v[24:25], 0, v[26:27]
	s_waitcnt lgkmcnt(0)
	v_add_f32_e32 v40, v40, v41
	v_mov_b32_e32 v41, v40
	s_nop 1
	v_permlane16_swap_b32_e32 v40, v41
	s_waitcnt lgkmcnt(0)
	v_add_f32_e32 v40, v40, v41
	ds_bpermute_b32 v41, v34, v40
	s_waitcnt lgkmcnt(0)
	v_add_f32_e32 v40, v40, v41
	ds_bpermute_b32 v41, v35, v40
	s_waitcnt lgkmcnt(0)
	v_add_f32_e32 v40, v40, v41
	ds_bpermute_b32 v41, v36, v40
	s_waitcnt lgkmcnt(0)
	v_add_f32_e32 v40, v40, v41
	ds_bpermute_b32 v41, v37, v40
	s_waitcnt lgkmcnt(0)
	v_add_f32_e32 v40, v40, v41
	v_fmamk_f32 v40, v40, 0x3a800000, v38
	v_mul_f32_e32 v41, 0x4f800000, v40
	v_cmp_gt_f32_e32 vcc, s6, v40
	v_lshlrev_b32_e32 v54, 16, v46
	s_nop 0
	v_cndmask_b32_e32 v40, v40, v41, vcc
	v_sqrt_f32_e32 v41, v40
	v_and_b32_e32 v55, 0xffff0000, v46
	v_lshlrev_b32_e32 v46, 16, v47
	v_and_b32_e32 v47, 0xffff0000, v47
	v_add_u32_e32 v50, -1, v41
	v_add_u32_e32 v51, 1, v41
	v_fma_f32 v52, -v50, v41, v40
	v_fma_f32 v53, -v51, v41, v40
	v_cmp_ge_f32_e64 s[2:3], 0, v52
	v_lshlrev_b32_e32 v56, 16, v48
	v_and_b32_e32 v57, 0xffff0000, v48
	v_cndmask_b32_e64 v41, v41, v50, s[2:3]
	v_cmp_lt_f32_e64 s[2:3], 0, v53
	v_lshlrev_b32_e32 v48, 16, v49
	v_and_b32_e32 v49, 0xffff0000, v49
	v_cndmask_b32_e64 v41, v41, v51, s[2:3]
	v_mul_f32_e32 v50, 0x37800000, v41
	v_cndmask_b32_e32 v41, v41, v50, vcc
	v_cmp_class_f32_e32 vcc, v40, v39
	v_pk_add_f32 v[46:47], v[16:17], v[46:47]
	v_pk_add_f32 v[54:55], v[18:19], v[54:55]
	v_cndmask_b32_e32 v40, v41, v40, vcc
	v_div_scale_f32 v41, s[2:3], v40, v40, 1.0
	v_rcp_f32_e32 v50, v41
	v_div_scale_f32 v51, vcc, 1.0, v40, 1.0
	v_pk_add_f32 v[58:59], v[16:17], v[48:49]
	v_fma_f32 v52, -v41, v50, 1.0
	v_fmac_f32_e32 v50, v52, v50
	v_mul_f32_e32 v52, v51, v50
	v_fma_f32 v53, -v41, v52, v51
	v_fmac_f32_e32 v52, v53, v50
	v_fma_f32 v41, -v41, v52, v51
	v_div_fmas_f32 v41, v41, v50, v52
	v_div_fixup_f32 v52, v41, v40, 1.0
	v_lshlrev_b32_e32 v40, 16, v42
	v_and_b32_e32 v41, 0xffff0000, v42
	v_lshlrev_b32_e32 v42, 16, v43
	v_and_b32_e32 v43, 0xffff0000, v43
	v_lshlrev_b32_e32 v50, 16, v44
	v_and_b32_e32 v51, 0xffff0000, v44
	v_lshlrev_b32_e32 v44, 16, v45
	v_and_b32_e32 v45, 0xffff0000, v45
	v_pk_add_f32 v[42:43], v[16:17], v[42:43]
	v_pk_add_f32 v[40:41], v[18:19], v[40:41]
	v_pk_add_f32 v[44:45], v[16:17], v[44:45]
	v_pk_add_f32 v[50:51], v[18:19], v[50:51]
	v_pk_mul_f32 v[40:41], v[40:41], v[52:53] op_sel_hi:[1,0]
	v_pk_mul_f32 v[42:43], v[42:43], v[52:53] op_sel_hi:[1,0]
	v_pk_mul_f32 v[48:49], v[50:51], v[52:53] op_sel_hi:[1,0]
	v_pk_mul_f32 v[44:45], v[44:45], v[52:53] op_sel_hi:[1,0]
	v_pk_mul_f32 v[54:55], v[54:55], v[52:53] op_sel_hi:[1,0]
	v_pk_mul_f32 v[50:51], v[46:47], v[52:53] op_sel_hi:[1,0]
	v_pk_mul_f32 v[42:43], v[2:3], v[42:43]
	v_pk_mul_f32 v[40:41], v[0:1], v[40:41]
	v_pk_mul_f32 v[46:47], v[6:7], v[44:45]
	v_pk_mul_f32 v[44:45], v[4:5], v[48:49]
	v_pk_mul_f32 v[50:51], v[10:11], v[50:51]
	v_pk_mul_f32 v[48:49], v[8:9], v[54:55]
	global_store_dwordx4 v[28:29], v[40:43], off offset:-3072 nt
	global_store_dwordx4 v[28:29], v[44:47], off offset:-2048 nt
	global_store_dwordx4 v[28:29], v[48:51], off offset:-1024 nt
	v_pk_add_f32 v[40:41], v[18:19], v[56:57]
	v_pk_mul_f32 v[42:43], v[58:59], v[52:53] op_sel_hi:[1,0]
	v_pk_mul_f32 v[40:41], v[40:41], v[52:53] op_sel_hi:[1,0]
	v_pk_mul_f32 v[42:43], v[14:15], v[42:43]
	v_pk_mul_f32 v[40:41], v[12:13], v[40:41]
	v_cmp_lt_i32_e32 vcc, s7, v160
	global_store_dwordx4 v[28:29], v[40:43], off nt
	s_or_b64 s[4:5], vcc, s[4:5]
	v_lshl_add_u64 v[28:29], v[28:29], 0, v[30:31]
	s_andn2_b64 exec, exec, s[4:5]
	s_cbranch_execz .LBB0_674
